# top-k search: waves that hold no keys (context units: only wave 0 has data) skip the candidate compares of every step
# baseline (speedup 1.0000x reference)
.LBB0_611:
	s_mul_i32 s6, s28, -3
	s_add_i32 s8, s6, 28
	s_cmp_lg_u32 s28, 10
	v_cndmask_b32_e64 v10, 0, 1, s[20:21]
	s_cselect_b64 s[24:25], -1, 0
	v_lshlrev_b32_e32 v10, 8, v10
	s_and_b64 s[6:7], s[24:25], exec
	v_add_u32_e32 v10, s45, v10
	s_cselect_b32 s29, s8, 0
	s_waitcnt vmcnt(0)
	s_cmp_eq_u64 s[22:23], 0
	s_cbranch_scc1 .Ltk_w5
	s_lshl_b32 s6, 1, s29
	s_or_b32 s26, s6, s38
	v_cmp_le_u32_e64 s[16:17], s26, v6
	v_cmp_le_u32_e64 s[18:19], s26, v7
	v_cmp_le_u32_e64 s[14:15], s26, v8
	v_cmp_le_u32_e64 s[12:13], s26, v9
	v_cmp_le_u32_e64 s[10:11], s26, v2
	v_cmp_le_u32_e64 s[8:9], s26, v3
	v_cmp_le_u32_e64 s[6:7], s26, v4
	v_cmp_le_u32_e32 vcc, s26, v5
	s_bcnt1_i32_b64 s16, s[16:17]
	s_bcnt1_i32_b64 s17, s[18:19]
	s_add_i32 s16, s17, s16
	s_bcnt1_i32_b64 s14, s[14:15]
	s_add_i32 s14, s16, s14
	s_bcnt1_i32_b64 s12, s[12:13]
	s_add_i32 s12, s14, s12
	s_bcnt1_i32_b64 s10, s[10:11]
	s_add_i32 s10, s12, s10
	s_bcnt1_i32_b64 s8, s[8:9]
	s_add_i32 s8, s10, s8
	s_bcnt1_i32_b64 s6, s[6:7]
	s_add_i32 s6, s8, s6
	s_bcnt1_i32_b64 s7, vcc
	s_add_i32 s6, s6, s7
	v_writelane_b32 v11, s6, 0
	s_cmp_eq_u64 s[24:25], 0
	s_cbranch_scc1 .Ltk_w5
	s_lshl_b32 s6, 2, s29
	s_or_b32 s26, s6, s38
	v_cmp_le_u32_e64 s[16:17], s26, v6
	v_cmp_le_u32_e64 s[18:19], s26, v7
	v_cmp_le_u32_e64 s[14:15], s26, v8
	v_cmp_le_u32_e64 s[12:13], s26, v9
	v_cmp_le_u32_e64 s[10:11], s26, v2
	v_cmp_le_u32_e64 s[8:9], s26, v3
	v_cmp_le_u32_e64 s[6:7], s26, v4
	v_cmp_le_u32_e32 vcc, s26, v5
	s_bcnt1_i32_b64 s16, s[16:17]
	s_bcnt1_i32_b64 s17, s[18:19]
	s_add_i32 s16, s17, s16
	s_bcnt1_i32_b64 s14, s[14:15]
	s_add_i32 s14, s16, s14
	s_bcnt1_i32_b64 s12, s[12:13]
	s_add_i32 s12, s14, s12
	s_bcnt1_i32_b64 s10, s[10:11]
	s_add_i32 s10, s12, s10
	s_bcnt1_i32_b64 s8, s[8:9]
	s_add_i32 s8, s10, s8
	s_bcnt1_i32_b64 s6, s[6:7]
	s_add_i32 s6, s8, s6
	s_bcnt1_i32_b64 s7, vcc
	s_add_i32 s6, s6, s7
	v_writelane_b32 v11, s6, 1
	s_lshl_b32 s6, 3, s29
	s_or_b32 s26, s6, s38
	v_cmp_le_u32_e64 s[16:17], s26, v6
	v_cmp_le_u32_e64 s[18:19], s26, v7
	v_cmp_le_u32_e64 s[14:15], s26, v8
	v_cmp_le_u32_e64 s[12:13], s26, v9
	v_cmp_le_u32_e64 s[10:11], s26, v2
	v_cmp_le_u32_e64 s[8:9], s26, v3
	v_cmp_le_u32_e64 s[6:7], s26, v4
	v_cmp_le_u32_e32 vcc, s26, v5
	s_bcnt1_i32_b64 s16, s[16:17]
	s_bcnt1_i32_b64 s17, s[18:19]
	s_add_i32 s16, s17, s16
	s_bcnt1_i32_b64 s14, s[14:15]
	s_add_i32 s14, s16, s14
	s_bcnt1_i32_b64 s12, s[12:13]
	s_add_i32 s12, s14, s12
	s_bcnt1_i32_b64 s10, s[10:11]
	s_add_i32 s10, s12, s10
	s_bcnt1_i32_b64 s8, s[8:9]
	s_add_i32 s8, s10, s8
	s_bcnt1_i32_b64 s6, s[6:7]
	s_add_i32 s6, s8, s6
	s_bcnt1_i32_b64 s7, vcc
	s_add_i32 s6, s6, s7
	v_writelane_b32 v11, s6, 2
	s_lshl_b32 s6, 4, s29
	s_or_b32 s26, s6, s38
	v_cmp_le_u32_e64 s[16:17], s26, v6
	v_cmp_le_u32_e64 s[18:19], s26, v7
	v_cmp_le_u32_e64 s[14:15], s26, v8
	v_cmp_le_u32_e64 s[12:13], s26, v9
	v_cmp_le_u32_e64 s[10:11], s26, v2
	v_cmp_le_u32_e64 s[8:9], s26, v3
	v_cmp_le_u32_e64 s[6:7], s26, v4
	v_cmp_le_u32_e32 vcc, s26, v5
	s_bcnt1_i32_b64 s16, s[16:17]
	s_bcnt1_i32_b64 s17, s[18:19]
	s_add_i32 s16, s17, s16
	s_bcnt1_i32_b64 s14, s[14:15]
	s_add_i32 s14, s16, s14
	s_bcnt1_i32_b64 s12, s[12:13]
	s_add_i32 s12, s14, s12
	s_bcnt1_i32_b64 s10, s[10:11]
	s_add_i32 s10, s12, s10
	s_bcnt1_i32_b64 s8, s[8:9]
	s_add_i32 s8, s10, s8
	s_bcnt1_i32_b64 s6, s[6:7]
	s_add_i32 s6, s8, s6
	s_bcnt1_i32_b64 s7, vcc
	s_add_i32 s6, s6, s7
	v_writelane_b32 v11, s6, 3
	s_lshl_b32 s6, 5, s29
	s_or_b32 s26, s6, s38
	v_cmp_le_u32_e64 s[16:17], s26, v6
	v_cmp_le_u32_e64 s[18:19], s26, v7
	v_cmp_le_u32_e64 s[14:15], s26, v8
	v_cmp_le_u32_e64 s[12:13], s26, v9
	v_cmp_le_u32_e64 s[10:11], s26, v2
	v_cmp_le_u32_e64 s[8:9], s26, v3
	v_cmp_le_u32_e64 s[6:7], s26, v4
	v_cmp_le_u32_e32 vcc, s26, v5
	s_bcnt1_i32_b64 s16, s[16:17]
	s_bcnt1_i32_b64 s17, s[18:19]
	s_add_i32 s16, s17, s16
	s_bcnt1_i32_b64 s14, s[14:15]
	s_add_i32 s14, s16, s14
	s_bcnt1_i32_b64 s12, s[12:13]
	s_add_i32 s12, s14, s12
	s_bcnt1_i32_b64 s10, s[10:11]
	s_add_i32 s10, s12, s10
	s_bcnt1_i32_b64 s8, s[8:9]
	s_add_i32 s8, s10, s8
	s_bcnt1_i32_b64 s6, s[6:7]
	s_add_i32 s6, s8, s6
	s_bcnt1_i32_b64 s7, vcc
	s_add_i32 s6, s6, s7
	v_writelane_b32 v11, s6, 4
	s_lshl_b32 s6, 6, s29
	s_or_b32 s26, s6, s38
	v_cmp_le_u32_e64 s[16:17], s26, v6
	v_cmp_le_u32_e64 s[18:19], s26, v7
	v_cmp_le_u32_e64 s[14:15], s26, v8
	v_cmp_le_u32_e64 s[12:13], s26, v9
	v_cmp_le_u32_e64 s[10:11], s26, v2
	v_cmp_le_u32_e64 s[8:9], s26, v3
	v_cmp_le_u32_e64 s[6:7], s26, v4
	v_cmp_le_u32_e32 vcc, s26, v5
	s_bcnt1_i32_b64 s16, s[16:17]
	s_bcnt1_i32_b64 s17, s[18:19]
	s_add_i32 s16, s17, s16
	s_bcnt1_i32_b64 s14, s[14:15]
	s_add_i32 s14, s16, s14
	s_bcnt1_i32_b64 s12, s[12:13]
	s_add_i32 s12, s14, s12
	s_bcnt1_i32_b64 s10, s[10:11]
	s_add_i32 s10, s12, s10
	s_bcnt1_i32_b64 s8, s[8:9]
	s_add_i32 s8, s10, s8
	s_bcnt1_i32_b64 s6, s[6:7]
	s_add_i32 s6, s8, s6
	s_bcnt1_i32_b64 s7, vcc
	s_add_i32 s6, s6, s7
	v_writelane_b32 v11, s6, 5
	s_lshl_b32 s6, 7, s29
	s_or_b32 s26, s6, s38
	v_cmp_le_u32_e64 s[16:17], s26, v6
	v_cmp_le_u32_e64 s[18:19], s26, v7
	v_cmp_le_u32_e64 s[14:15], s26, v8
	v_cmp_le_u32_e64 s[12:13], s26, v9
	v_cmp_le_u32_e64 s[10:11], s26, v2
	v_cmp_le_u32_e64 s[8:9], s26, v3
	v_cmp_le_u32_e64 s[6:7], s26, v4
	v_cmp_le_u32_e32 vcc, s26, v5
	s_bcnt1_i32_b64 s16, s[16:17]
	s_bcnt1_i32_b64 s17, s[18:19]
	s_add_i32 s16, s17, s16
	s_bcnt1_i32_b64 s14, s[14:15]
	s_add_i32 s14, s16, s14
	s_bcnt1_i32_b64 s12, s[12:13]
	s_add_i32 s12, s14, s12
	s_bcnt1_i32_b64 s10, s[10:11]
	s_add_i32 s10, s12, s10
	s_bcnt1_i32_b64 s8, s[8:9]
	s_add_i32 s8, s10, s8
	s_bcnt1_i32_b64 s6, s[6:7]
	s_add_i32 s6, s8, s6
	s_bcnt1_i32_b64 s7, vcc
	s_add_i32 s6, s6, s7
	v_writelane_b32 v11, s6, 6
